# scan state-update LDS reads pipelined six deep on top of scan wait relaxations, EpiR and attention-tail batching
# speedup vs baseline: 1.0073x; 1.0073x over previous
; #define MFMA16(a, b, c) __builtin_amdgcn_mfma_f32_16x16x32_bf16((a), (b), (c), 0, 0, 0)
; DI unsigned pk2(float lo, float hi) { const f32x2 v = {lo, hi}; const bf16x2_t b = __builtin_convertvector(v, bf16x2_t); return __builtin_bit_cast(unsigned, b); }
; template <int C> DI void gdn_scan_item(const Params& p, int l, int b, int h, unsigned char* smem) {
;     ...
; #pragma unroll
;         for (int c = 0; c < 8; ++c) S[c] = S[c] * eg;
; #pragma unroll
;         for (int s = 0; s < KS2; ++s) {
; #pragma unroll
;             for (int c = 0; c < 8; ++c) { const bf16x8 bb = *(const bf16x8*)(VnT + (16 * c + l15) * 80 + 32 * s + 8 * gq); S[c] = MFMA16(aT[s], bb, S[c]); } }
; #pragma unroll
;         for (int c = 0; c < 8; ++c) { u32x2 o; o.x = pk2(S[c][0], S[c][1]); o.y = pk2(S[c][2], S[c][3]); *(u32x2*)(SbT + (16 * c + l15) * 144 + 16 * w + 4 * gq) = o; }
.LBB0_679:
	s_or_b64 exec, exec, s[14:15]
	s_waitcnt lgkmcnt(0)
	ds_read_b128 v[88:91], v185 offset:36864
	ds_read_b128 v[92:95], v185 offset:39424
	ds_read_b128 v[96:99], v185 offset:41984
	ds_read_b128 v[100:103], v185 offset:44544
	ds_read_b128 v[104:107], v185 offset:47104
	ds_read_b128 v[108:111], v185 offset:49664
	v_pk_mul_f32 v[34:35], v[34:35], v[154:155] op_sel_hi:[1,0]
	v_pk_mul_f32 v[32:33], v[32:33], v[154:155] op_sel_hi:[1,0]
	v_pk_mul_f32 v[38:39], v[38:39], v[154:155] op_sel_hi:[1,0]
	v_pk_mul_f32 v[36:37], v[36:37], v[154:155] op_sel_hi:[1,0]
	v_pk_mul_f32 v[42:43], v[42:43], v[154:155] op_sel_hi:[1,0]
	v_pk_mul_f32 v[40:41], v[40:41], v[154:155] op_sel_hi:[1,0]
	v_pk_mul_f32 v[46:47], v[46:47], v[154:155] op_sel_hi:[1,0]
	v_pk_mul_f32 v[44:45], v[44:45], v[154:155] op_sel_hi:[1,0]
	v_pk_mul_f32 v[50:51], v[50:51], v[154:155] op_sel_hi:[1,0]
	v_pk_mul_f32 v[48:49], v[48:49], v[154:155] op_sel_hi:[1,0]
	v_pk_mul_f32 v[54:55], v[54:55], v[154:155] op_sel_hi:[1,0]
	v_pk_mul_f32 v[52:53], v[52:53], v[154:155] op_sel_hi:[1,0]
	v_pk_mul_f32 v[58:59], v[58:59], v[154:155] op_sel_hi:[1,0]
	v_pk_mul_f32 v[56:57], v[56:57], v[154:155] op_sel_hi:[1,0]
	v_pk_mul_f32 v[62:63], v[62:63], v[154:155] op_sel_hi:[1,0]
	v_pk_mul_f32 v[60:61], v[60:61], v[154:155] op_sel_hi:[1,0]
	s_mov_b32 s4, 0x358637bd
	s_add_i32 s0, s0, 64
	s_add_i32 s17, s17, 1
	s_waitcnt vmcnt(41) lgkmcnt(5)
	v_mfma_f32_16x16x32_bf16 v[32:35], v[68:71], v[88:91], v[32:35]
	ds_read_b128 v[88:91], v185 offset:52224
	s_waitcnt lgkmcnt(5)
	v_mfma_f32_16x16x32_bf16 v[36:39], v[68:71], v[92:95], v[36:39]
	ds_read_b128 v[92:95], v185 offset:54784
	s_waitcnt lgkmcnt(5)
	v_mfma_f32_16x16x32_bf16 v[40:43], v[68:71], v[96:99], v[40:43]
	s_waitcnt lgkmcnt(4)
	v_mfma_f32_16x16x32_bf16 v[44:47], v[68:71], v[100:103], v[44:47]
	s_waitcnt lgkmcnt(3)
	v_mfma_f32_16x16x32_bf16 v[48:51], v[68:71], v[104:107], v[48:51]
	s_waitcnt lgkmcnt(2)
	v_mfma_f32_16x16x32_bf16 v[52:55], v[68:71], v[108:111], v[52:55]
	s_waitcnt lgkmcnt(1)
	v_mfma_f32_16x16x32_bf16 v[56:59], v[68:71], v[88:91], v[56:59]
	s_waitcnt lgkmcnt(0)
	v_mfma_f32_16x16x32_bf16 v[60:63], v[68:71], v[92:95], v[60:63]
	ds_read_b128 v[68:71], v185 offset:36928
	ds_read_b128 v[88:91], v185 offset:39488
	s_add_u32 s12, s12, 4
	s_addc_u32 s13, s13, 0
	s_waitcnt vmcnt(40) lgkmcnt(1)
	v_mfma_f32_16x16x32_bf16 v[32:35], v[64:67], v[68:71], v[32:35]
	ds_read_b128 v[68:71], v185 offset:42048
	ds_read_b128 v[92:95], v185 offset:44608
	ds_read_b128 v[96:99], v185 offset:47168
	s_cmpk_lg_i32 s0, 0x1000
	s_waitcnt vmcnt(7)
	v_mov_b32_e32 v170, v197
	s_waitcnt lgkmcnt(3)
	v_mfma_f32_16x16x32_bf16 v[36:39], v[64:67], v[88:91], v[36:39]
	ds_read_b128 v[88:91], v185 offset:49728
	ds_read_b128 v[100:103], v185 offset:52288
	ds_read_b128 v[104:107], v185 offset:54848
	s_waitcnt vmcnt(6)
	v_mov_b32_e32 v171, v198
	v_mov_b32_e32 v168, v187
	s_waitcnt lgkmcnt(5)
	v_mfma_f32_16x16x32_bf16 v[40:43], v[64:67], v[68:71], v[40:43]
	v_cvt_pk_bf16_f32 v68, v32, v33
	v_cvt_pk_bf16_f32 v69, v34, v35
	v_cvt_pk_bf16_f32 v70, v36, v37
	s_waitcnt lgkmcnt(4)
	v_mfma_f32_16x16x32_bf16 v[44:47], v[64:67], v[92:95], v[44:47]
	v_cvt_pk_bf16_f32 v71, v38, v39
	ds_write2st64_b64 v186, v[68:69], v[70:71] offset1:9
	s_nop 0
	v_cvt_pk_bf16_f32 v68, v40, v41
	s_waitcnt lgkmcnt(4)
	v_mfma_f32_16x16x32_bf16 v[48:51], v[64:67], v[96:99], v[48:51]
	v_cvt_pk_bf16_f32 v69, v42, v43
	s_nop 0
	v_cvt_pk_bf16_f32 v70, v44, v45
	v_cvt_pk_bf16_f32 v71, v46, v47
	s_waitcnt lgkmcnt(3)
	v_mfma_f32_16x16x32_bf16 v[52:55], v[64:67], v[88:91], v[52:55]
	ds_write2st64_b64 v186, v[68:69], v[70:71] offset0:18 offset1:27
	s_nop 0
	v_cvt_pk_bf16_f32 v68, v48, v49
	v_cvt_pk_bf16_f32 v69, v50, v51
	s_waitcnt lgkmcnt(3)
	v_mfma_f32_16x16x32_bf16 v[56:59], v[64:67], v[100:103], v[56:59]
	v_lshlrev_b32_e32 v96, 16, v226
	s_nop 0
	v_cvt_pk_bf16_f32 v70, v52, v53
	v_cvt_pk_bf16_f32 v71, v54, v55
	s_waitcnt lgkmcnt(2)
	v_mfma_f32_16x16x32_bf16 v[60:63], v[64:67], v[104:107], v[60:63]
	ds_write2st64_b64 v186, v[68:69], v[70:71] offset0:36 offset1:45
	s_nop 0
	v_cvt_pk_bf16_f32 v64, v56, v57
	v_cvt_pk_bf16_f32 v65, v58, v59
	v_add_u32_e32 v68, 0, v179
	v_add_u32_e32 v70, 0, v180
	s_nop 1
	v_cvt_pk_bf16_f32 v66, v60, v61
	v_cvt_pk_bf16_f32 v67, v62, v63
	ds_write2st64_b64 v186, v[64:65], v[66:67] offset0:54 offset1:63
	s_waitcnt lgkmcnt(0)
	s_barrier
; DI float bf2f(unsigned short b) { return __uint_as_float(((unsigned)b) << 16); }
; DI unsigned short f2bf(float f) { unsigned u = __float_as_uint(f); u += 0x7fffu + ((u >> 16) & 1u); return (unsigned short)(u >> 16); }
; template <int C> DI void gdn_scan_item(const Params& p, int l, int b, int h, unsigned char* smem) {
;     ...
;         __syncthreads();
; #pragma unroll
;         for (int r = 0; r < 4; ++r) { const int i = 16 * ti + 4 * gq + r; float tot = 0.f;
; #pragma unroll
;             for (int d = 0; d < NDVG; ++d) tot += RS[i * 4 + d];
;             const float rs = rsqrtf(tot * (1.0f / 128.0f) + EPS);
; #pragma unroll
;             for (int t = 0; t < TPW; ++t) { const int dv = 16 * (dvg * TPW + t) + l15; const float sz = bf2f(szr[t][r]);
;                 MIX[(size_t)(r0c + i) * KOUT + 512 + h * 128 + dv] = f2bf(a2[t][r] * rs * nw[dv] * sz); } }
; #pragma unroll
;         for (int s = 0; s < 4; ++s) { cW[s] = nW[s]; cQ[s] = nQ[s]; }
; #pragma unroll
;         for (int t = 0; t < TPW; ++t)
; #pragma unroll
;             for (int r = 0; r < 4; ++r) cU[t][r] = nU[t][r];
	v_add_u32_e32 v66, 0, v178
	ds_read_b64 v[66:67], v66 offset:57344
	ds_read_b64 v[68:69], v68 offset:57344
	v_lshl_add_u64 v[64:65], v[126:127], 0, v[138:139]
	v_add_u32_e32 v88, 0, v181
	ds_read_b64 v[70:71], v70 offset:57344
	ds_read_b64 v[88:89], v88 offset:57344
	s_waitcnt lgkmcnt(3)
	v_mov_b32_e32 v91, v66
	s_waitcnt lgkmcnt(2)
	v_mov_b32_e32 v90, v68
	v_pk_add_f32 v[90:91], v[90:91], 0 op_sel_hi:[1,0]
	v_mov_b32_e32 v66, v69
	v_pk_add_f32 v[66:67], v[90:91], v[66:67]
	v_mov_b64_e32 v[68:69], s[4:5]
	s_brev_b32 s4, 60
	v_pk_fma_f32 v[66:67], v[66:67], s[4:5], v[68:69] op_sel_hi:[1,0,0]
	v_lshlrev_b32_e32 v91, 16, v224
	v_mul_f32_e32 v90, 0x4b800000, v67
	v_cmp_gt_f32_e32 vcc, s79, v67
	v_lshlrev_b32_e32 v97, 16, v225
	v_mov_b64_e32 v[102:103], v[18:19]
	v_cndmask_b32_e32 v67, v67, v90, vcc
	v_rsq_f32_e32 v67, v67
	v_lshlrev_b32_e32 v90, 16, v223
	v_mov_b64_e32 v[106:107], v[2:3]
	v_mov_b64_e32 v[100:101], v[16:17]
	v_mul_f32_e32 v98, 0x45800000, v67
	v_cndmask_b32_e32 v67, v67, v98, vcc
	v_mul_f32_e32 v72, v72, v67
	v_cmp_gt_f32_e32 vcc, s79, v66
	v_mov_b64_e32 v[104:105], v[0:1]
	v_mov_b32_e32 v169, v188
	s_waitcnt vmcnt(5)
	v_mov_b32_e32 v166, v199
	s_waitcnt vmcnt(4)
	v_mov_b32_e32 v167, v209
	v_mov_b32_e32 v164, v189
	v_mov_b32_e32 v165, v190
	s_waitcnt vmcnt(3)
	v_mov_b32_e32 v162, v210
	s_waitcnt vmcnt(2)
	v_mov_b32_e32 v163, v211
	v_mov_b32_e32 v160, v192
	v_mov_b32_e32 v161, v193
	s_waitcnt vmcnt(0)
	v_mov_b32_e32 v158, v213
	v_mov_b32_e32 v159, v212
	v_mov_b32_e32 v156, v196
	v_mov_b32_e32 v157, v195
	v_mul_f32_e32 v72, v144, v72
	v_mul_f32_e32 v72, v72, v96
	v_bfe_u32 v96, v72, 16, 1
	v_add3_u32 v72, v72, v96, s59
	global_store_short_d16_hi v[64:65], v72, off
	v_mul_f32_e32 v72, v76, v67
	v_mul_f32_e32 v72, v204, v72
	v_mul_f32_e32 v72, v72, v90
	v_bfe_u32 v76, v72, 16, 1
	v_add3_u32 v72, v72, v76, s59
	global_store_short_d16_hi v[64:65], v72, off offset:32
	v_mul_f32_e32 v72, v80, v67
	v_mul_f32_e32 v72, v227, v72
	v_mul_f32_e32 v72, v72, v91
	v_bfe_u32 v76, v72, 16, 1
	v_add3_u32 v72, v72, v76, s59
	global_store_short_d16_hi v[64:65], v72, off offset:64
	v_mul_f32_e32 v72, 0x4b800000, v66
	v_mul_f32_e32 v67, v84, v67
	v_cndmask_b32_e32 v66, v66, v72, vcc
	v_mul_f32_e32 v67, v124, v67
	v_rsq_f32_e32 v66, v66
	v_mul_f32_e32 v67, v67, v97
	v_bfe_u32 v72, v67, 16, 1
	v_add3_u32 v67, v67, v72, s59
	global_store_short_d16_hi v[64:65], v67, off offset:96
	v_mul_f32_e32 v64, 0x45800000, v66
	v_cndmask_b32_e32 v66, v66, v64, vcc
	v_mul_f32_e32 v65, v73, v66
	v_lshlrev_b32_e32 v64, 16, v222
	v_mul_f32_e32 v65, v144, v65
	v_mul_f32_e32 v64, v65, v64
	v_bfe_u32 v65, v64, 16, 1
	v_add3_u32 v67, v64, v65, s59
	v_lshl_add_u64 v[64:65], v[126:127], 0, v[136:137]
	v_mul_f32_e32 v72, v77, v66
	global_store_short_d16_hi v[64:65], v67, off
	v_lshlrev_b32_e32 v67, 16, v221
	v_mul_f32_e32 v72, v204, v72
	v_mul_f32_e32 v67, v72, v67
	v_bfe_u32 v72, v67, 16, 1
	v_add3_u32 v67, v67, v72, s59
	v_mul_f32_e32 v72, v81, v66
	global_store_short_d16_hi v[64:65], v67, off offset:32
	v_lshlrev_b32_e32 v67, 16, v220
	v_mul_f32_e32 v72, v227, v72
	v_mul_f32_e32 v67, v72, v67
	v_bfe_u32 v72, v67, 16, 1
	v_add3_u32 v67, v67, v72, s59
	v_mul_f32_e32 v66, v85, v66
	global_store_short_d16_hi v[64:65], v67, off offset:64
	v_lshlrev_b32_e32 v67, 16, v219
	v_mul_f32_e32 v66, v124, v66
	v_mul_f32_e32 v66, v66, v67
	v_bfe_u32 v67, v66, 16, 1
	v_add3_u32 v66, v66, v67, s59
	global_store_short_d16_hi v[64:65], v66, off offset:96
	s_waitcnt lgkmcnt(0)
	v_mov_b32_e32 v66, v88
	v_mov_b32_e32 v67, v70
	v_pk_add_f32 v[66:67], v[66:67], 0 op_sel_hi:[1,0]
	v_mov_b32_e32 v70, v89
	v_pk_add_f32 v[66:67], v[66:67], v[70:71]
	v_lshlrev_b32_e32 v72, 16, v218
	v_pk_fma_f32 v[66:67], v[66:67], s[4:5], v[68:69] op_sel_hi:[1,0,0]
	v_lshl_add_u64 v[64:65], v[126:127], 0, v[134:135]
	v_mul_f32_e32 v68, 0x4b800000, v67
	v_cmp_gt_f32_e32 vcc, s79, v67
	v_lshlrev_b32_e32 v69, 16, v216
	v_lshlrev_b32_e32 v70, 16, v217
	v_cndmask_b32_e32 v67, v67, v68, vcc
	v_rsq_f32_e32 v67, v67
	v_lshlrev_b32_e32 v68, 16, v215
	s_mov_b64 s[4:5], 0x16000
	v_mov_b64_e32 v[90:91], v[22:23]
	v_mul_f32_e32 v71, 0x45800000, v67
	v_cndmask_b32_e32 v67, v67, v71, vcc
	v_mul_f32_e32 v71, v74, v67
	v_mul_f32_e32 v71, v144, v71
	v_mul_f32_e32 v71, v71, v72
	v_bfe_u32 v72, v71, 16, 1
	v_add3_u32 v71, v71, v72, s59
	global_store_short_d16_hi v[64:65], v71, off
	v_mul_f32_e32 v71, v78, v67
	v_mul_f32_e32 v71, v204, v71
	v_mul_f32_e32 v68, v71, v68
	v_bfe_u32 v71, v68, 16, 1
	v_add3_u32 v68, v68, v71, s59
	global_store_short_d16_hi v[64:65], v68, off offset:32
	v_mul_f32_e32 v68, v82, v67
	v_mul_f32_e32 v68, v227, v68
	v_mul_f32_e32 v68, v68, v69
	v_bfe_u32 v69, v68, 16, 1
	v_add3_u32 v68, v68, v69, s59
	global_store_short_d16_hi v[64:65], v68, off offset:64
	v_mul_f32_e32 v68, 0x4b800000, v66
	v_cmp_gt_f32_e32 vcc, s79, v66
	v_mul_f32_e32 v67, v86, v67
	v_mul_f32_e32 v67, v124, v67
	v_cndmask_b32_e32 v66, v66, v68, vcc
	v_rsq_f32_e32 v66, v66
	v_mul_f32_e32 v67, v67, v70
	v_bfe_u32 v68, v67, 16, 1
	v_add3_u32 v67, v67, v68, s59
	global_store_short_d16_hi v[64:65], v67, off offset:96
	v_mul_f32_e32 v64, 0x45800000, v66
	v_cndmask_b32_e32 v66, v66, v64, vcc
	v_mul_f32_e32 v65, v75, v66
	v_lshlrev_b32_e32 v64, 16, v214
	v_mul_f32_e32 v65, v144, v65
	v_mul_f32_e32 v64, v65, v64
	v_bfe_u32 v65, v64, 16, 1
	v_add3_u32 v67, v64, v65, s59
	v_lshl_add_u64 v[64:65], v[126:127], 0, v[132:133]
	v_mul_f32_e32 v68, v79, v66
	global_store_short_d16_hi v[64:65], v67, off
	v_lshlrev_b32_e32 v67, 16, v208
	v_mul_f32_e32 v68, v204, v68
	v_mul_f32_e32 v67, v68, v67
	v_bfe_u32 v68, v67, 16, 1
	v_add3_u32 v67, v67, v68, s59
	v_mul_f32_e32 v68, v83, v66
	global_store_short_d16_hi v[64:65], v67, off offset:32
	v_lshlrev_b32_e32 v67, 16, v194
	v_mul_f32_e32 v68, v227, v68
	v_mul_f32_e32 v67, v68, v67
	v_bfe_u32 v68, v67, 16, 1
	v_add3_u32 v67, v67, v68, s59
	v_mul_f32_e32 v66, v87, v66
	global_store_short_d16_hi v[64:65], v67, off offset:64
	v_lshlrev_b32_e32 v67, 16, v191
	v_mul_f32_e32 v66, v124, v66
	v_mul_f32_e32 v66, v66, v67
	v_bfe_u32 v67, v66, 16, 1
	v_mov_b64_e32 v[82:83], v[30:31]
	v_mov_b64_e32 v[74:75], v[26:27]
	v_mov_b64_e32 v[94:95], v[6:7]
	v_mov_b64_e32 v[86:87], v[10:11]
	v_mov_b64_e32 v[78:79], v[14:15]
	v_add3_u32 v66, v66, v67, s59
	v_lshl_add_u64 v[128:129], v[128:129], 0, s[4:5]
	v_lshl_add_u64 v[130:131], v[130:131], 0, s[4:5]
	v_mov_b64_e32 v[88:89], v[20:21]
	v_mov_b64_e32 v[80:81], v[28:29]
	v_mov_b64_e32 v[72:73], v[24:25]
	v_mov_b64_e32 v[92:93], v[4:5]
	v_mov_b64_e32 v[84:85], v[8:9]
	v_mov_b64_e32 v[76:77], v[12:13]
	global_store_short_d16_hi v[64:65], v66, off offset:96
	s_cbranch_scc0 .LBB0_684
